# v12 + grid barrier: non-leader workgroups poll the cross-XCD generation word directly (skip per-XCD release hop)
# baseline (speedup 1.0000x reference)
; __device__ __forceinline__ unsigned xb_ld(unsigned* p)              { return __hip_atomic_load(p, __ATOMIC_RELAXED, __HIP_MEMORY_SCOPE_AGENT); }
; __device__ __forceinline__ unsigned xb_add(unsigned* p, unsigned v) { return __hip_atomic_fetch_add(p, v, __ATOMIC_RELAXED, __HIP_MEMORY_SCOPE_AGENT); }
; #define XB_SPIN(cond, bar) do { unsigned _sp = 0; while (cond) { __builtin_amdgcn_s_sleep(4); \
;     if ((++_sp & 255u) == 0u) { if (xb_ld(&(bar)[XB_TMO])) break; if (_sp > XB_SPIN_CAP) { atomicAdd(&(bar)[XB_TMO], 1u); break; } } } } while (0)
; __device__ __forceinline__ void xcd_barrier(const XcdBarrier& b) {
;     ...
;         unsigned nloc = b.st[0], nx = b.st[1];
;         if (nloc == 0u) { xcd_barrier_complete(bar, b.x, nloc, nx); b.st[0] = nloc; b.st[1] = nx; }
;         const unsigned old = xb_add(&bar[XB_XSUB(b.x)], 1u);
;         const unsigned gen = old / nloc;
;         if (old + 1u == (gen + 1u) * nloc) {
;             __builtin_amdgcn_fence(__ATOMIC_RELEASE, "agent");
;             asm volatile("s_waitcnt vmcnt(0)" ::: "memory");
;             const unsigned og = xb_add(&bar[XB_TOP], 1u);
;             const unsigned tg = og / nx;
;             if (og + 1u == (tg + 1u) * nx) xb_add(&bar[XB_TOPGEN], 1u);
;             else XB_SPIN(xb_ld(&bar[XB_TOPGEN]) == tg, bar);
;             __builtin_amdgcn_fence(__ATOMIC_ACQUIRE, "agent");
;             xb_add(&bar[XB_XGEN(b.x)], 1u);
;             asm volatile("s_waitcnt vmcnt(0)" ::: "memory");
;         } else {
;             XB_SPIN(xb_ld(&bar[XB_XGEN(b.x)]) == gen, bar);
;             __builtin_amdgcn_fence(__ATOMIC_ACQUIRE, "agent");
.LBB0_628:
	s_or_b64 exec, exec, s[2:3]
	v_cvt_f32_u32_e32 v9, v3
	s_waitcnt vmcnt(0)
	v_readfirstlane_b32 s2, v8
	v_sub_u32_e32 v8, 0, v3
	v_rcp_iflag_f32_e32 v9, v9
	v_add_u32_e32 v10, s2, v0
	v_mul_f32_e32 v9, 0x4f7ffffe, v9
	v_cvt_u32_f32_e32 v9, v9
	v_mul_lo_u32 v0, v8, v9
	v_mul_hi_u32 v0, v9, v0
	v_add_u32_e32 v0, v9, v0
	v_mul_hi_u32 v0, v10, v0
	v_mul_lo_u32 v8, v0, v3
	v_sub_u32_e32 v8, v10, v8
	v_add_u32_e32 v9, 1, v0
	v_cmp_ge_u32_e32 vcc, v8, v3
	s_nop 1
	v_cndmask_b32_e32 v0, v0, v9, vcc
	v_sub_u32_e32 v9, v8, v3
	v_cndmask_b32_e32 v8, v8, v9, vcc
	v_add_u32_e32 v9, 1, v0
	v_cmp_ge_u32_e32 vcc, v8, v3
	v_add_u32_e32 v8, 1, v10
	s_nop 0
	v_cndmask_b32_e32 v0, v0, v9, vcc
	v_mul_lo_u32 v9, v3, v0
	v_add_u32_e32 v3, v9, v3
	v_cmp_ne_u32_e32 vcc, v8, v3
	s_and_saveexec_b64 s[2:3], vcc
	s_xor_b64 s[2:3], exec, s[2:3]
	s_cbranch_execz .LBB0_642
	v_readlane_b32 s4, v251, 43
	v_readlane_b32 s5, v251, 44
	s_waitcnt lgkmcnt(0)
	s_nop 3
	global_load_dword v2, v1, s[4:5] sc1
	s_waitcnt vmcnt(0)
	v_cmp_eq_u32_e32 vcc, v2, v0
	s_and_saveexec_b64 s[4:5], vcc
	s_cbranch_execz .LBB0_641
	s_mov_b32 s20, 1
	s_mov_b64 s[6:7], 0
	s_branch .LBB0_632
